# FFN-in load balance: 5 full units + one half-row unit per workgroup
# baseline (speedup 1.0000x reference)
.LBB0_661:
	s_add_i32 s79, s79, 1
	s_mul_i32 s6, s79, s78
	s_mul_hi_u32 s10, s79, s4
	s_add_i32 s10, s10, s6
	s_mul_i32 s6, s79, s4
	s_add_u32 s62, s6, s5
	s_addc_u32 s63, s10, s8
	v_mov_b64_e32 v[4:5], 0x600
	v_cmp_lt_i64_e64 s[12:13], s[62:63], v[4:5]
	v_mov_b64_e32 v[4:5], 0x5ff
	v_cmp_gt_i64_e32 vcc, s[62:63], v[4:5]
	s_cbranch_vccnz .LBB0_663
	s_mov_b32 s60, s66
	s_add_i32 s58, s14, 4
	s_cmp_eq_u32 s79, 5
	s_cbranch_scc0 .Lh4_nomap
	s_sub_i32 s58, s58, 20
	s_and_b32 s99, s58, 1
	s_lshr_b32 s58, s58, 1
	s_add_i32 s58, s58, 20
.Lh4_nomap:
.LBB0_663:
	s_ashr_i32 s61, s60, 31
	s_lshl_b64 s[10:11], s[60:61], 19
	s_add_u32 s62, s21, s10
	s_addc_u32 s63, s24, s11
	s_and_b64 s[10:11], s[12:13], exec
	s_cselect_b32 s10, s63, s69
	s_cselect_b32 s11, s62, s68
	s_ashr_i32 s59, s58, 31
	s_lshl_b64 s[64:65], s[58:59], 19
	s_add_u32 s64, s27, s64
	s_addc_u32 s65, s34, s65
	s_and_b64 s[72:73], s[12:13], exec
	s_cselect_b32 s15, s65, s71
	s_cselect_b32 s59, s64, s70
	s_add_u32 s68, s68, 0x40080
	s_addc_u32 s69, s69, 0
	s_add_u32 s61, s70, 0x100
	s_addc_u32 s67, s71, 0
	s_mov_b32 s80, -2
	s_cmp_eq_u32 s79, 6
	s_cbranch_scc1 .Lh4_unit
	s_add_u32 s6, s68, 0xfffc0080
	s_addc_u32 s33, s69, -1
	s_add_i32 s82, 0, 0x10000
	s_cmp_eq_u32 s80, 12
	s_cselect_b32 s73, s10, s33
	s_cselect_b32 s72, s11, s6
	v_add_u32_e32 v2, s82, v148
	s_cselect_b32 s71, s15, s67
	s_cselect_b32 s70, s59, s61
	s_add_i32 s6, 0, 0x14000
	ds_read_b128 v[152:155], v2
	ds_read_b128 v[156:159], v2 offset:1024
	ds_read_b128 v[160:163], v2 offset:2048
	ds_read_b128 v[168:171], v2 offset:3072
	v_add_u32_e32 v2, s6, v148
	ds_read_b128 v[174:177], v2
	ds_read_b128 v[178:181], v2 offset:1024
	ds_read_b128 v[182:185], v2 offset:2048
	ds_read_b128 v[186:189], v2 offset:3072
	v_lshl_add_u64 v[146:147], s[68:69], 0, v[142:143]
	s_add_i32 m0, s35, 0xc000
	ds_read_b128 v[200:203], v151
	ds_read_b128 v[204:207], v151 offset:1024
	ds_read_b128 v[208:211], v151 offset:2048
	ds_read_b128 v[212:215], v151 offset:3072
	ds_read_b128 v[216:219], v151 offset:4096
	ds_read_b128 v[220:223], v151 offset:5120
	ds_read_b128 v[224:227], v151 offset:6144
	ds_read_b128 v[228:231], v151 offset:7168
	global_load_lds_dwordx4 v[146:147], off
	v_lshl_add_u64 v[146:147], s[68:69], 0, v[144:145]
	s_add_i32 m0, s35, 0xe000
	s_nop 0
	global_load_lds_dwordx4 v[146:147], off
	s_waitcnt vmcnt(8)
	s_waitcnt lgkmcnt(0)
	s_barrier
	s_waitcnt lgkmcnt(0)
	v_mfma_f32_16x16x32_bf16 v[128:131], v[152:155], v[200:203], 0
	v_mfma_f32_16x16x32_bf16 v[120:123], v[160:163], v[200:203], 0
	v_mfma_f32_16x16x32_bf16 v[112:115], v[152:155], v[208:211], 0
	v_mfma_f32_16x16x32_bf16 v[104:107], v[160:163], v[208:211], 0
	v_mfma_f32_16x16x32_bf16 v[96:99], v[152:155], v[216:219], 0
	v_mfma_f32_16x16x32_bf16 v[88:91], v[160:163], v[216:219], 0
	v_mfma_f32_16x16x32_bf16 v[80:83], v[152:155], v[224:227], 0
	v_mfma_f32_16x16x32_bf16 v[72:75], v[160:163], v[224:227], 0
	v_mfma_f32_16x16x32_bf16 v[128:131], v[156:159], v[204:207], v[128:131]
	v_mfma_f32_16x16x32_bf16 v[120:123], v[168:171], v[204:207], v[120:123]
	v_mfma_f32_16x16x32_bf16 v[112:115], v[156:159], v[212:215], v[112:115]
	v_mfma_f32_16x16x32_bf16 v[104:107], v[168:171], v[212:215], v[104:107]
	v_mfma_f32_16x16x32_bf16 v[96:99], v[156:159], v[220:223], v[96:99]
	v_mfma_f32_16x16x32_bf16 v[88:91], v[168:171], v[220:223], v[88:91]
	v_mfma_f32_16x16x32_bf16 v[80:83], v[156:159], v[228:231], v[80:83]
	v_mfma_f32_16x16x32_bf16 v[72:75], v[168:171], v[228:231], v[72:75]
	v_mfma_f32_16x16x32_bf16 v[124:127], v[174:177], v[200:203], 0
	v_mfma_f32_16x16x32_bf16 v[116:119], v[182:185], v[200:203], 0
	v_mfma_f32_16x16x32_bf16 v[108:111], v[174:177], v[208:211], 0
	v_mfma_f32_16x16x32_bf16 v[100:103], v[182:185], v[208:211], 0
	v_mfma_f32_16x16x32_bf16 v[92:95], v[174:177], v[216:219], 0
	v_mfma_f32_16x16x32_bf16 v[84:87], v[182:185], v[216:219], 0
	v_mfma_f32_16x16x32_bf16 v[76:79], v[174:177], v[224:227], 0
	v_mfma_f32_16x16x32_bf16 v[68:71], v[182:185], v[224:227], 0
	v_mfma_f32_16x16x32_bf16 v[124:127], v[178:181], v[204:207], v[124:127]
	v_mfma_f32_16x16x32_bf16 v[116:119], v[186:189], v[204:207], v[116:119]
	v_mfma_f32_16x16x32_bf16 v[108:111], v[178:181], v[212:215], v[108:111]
	v_mfma_f32_16x16x32_bf16 v[100:103], v[186:189], v[212:215], v[100:103]
	v_mfma_f32_16x16x32_bf16 v[92:95], v[178:181], v[220:223], v[92:95]
	v_mfma_f32_16x16x32_bf16 v[84:87], v[186:189], v[220:223], v[84:87]
	v_mfma_f32_16x16x32_bf16 v[76:79], v[178:181], v[228:231], v[76:79]
	v_mfma_f32_16x16x32_bf16 v[68:71], v[186:189], v[228:231], v[68:71]
	s_barrier
	s_add_i32 s33, s82, s20
	v_lshl_add_u64 v[146:147], s[70:71], 0, v[134:135]
	s_mov_b32 m0, s33
	ds_read_b128 v[200:203], v151 offset:16384
	ds_read_b128 v[204:207], v151 offset:17408
	ds_read_b128 v[208:211], v151 offset:18432
	ds_read_b128 v[212:215], v151 offset:19456
	ds_read_b128 v[216:219], v151 offset:20480
	ds_read_b128 v[220:223], v151 offset:21504
	ds_read_b128 v[224:227], v151 offset:22528
	ds_read_b128 v[228:231], v151 offset:23552
	global_load_lds_dwordx4 v[146:147], off
	s_add_i32 m0, s33, 0x2000
	s_add_u32 s82, s70, 0x40000
	v_lshl_add_u64 v[164:165], s[70:71], 0, v[138:139]
	s_addc_u32 s83, s71, 0
	s_add_i32 s6, s6, s20
	global_load_lds_dwordx4 v[164:165], off
	v_lshl_add_u64 v[232:233], s[82:83], 0, v[134:135]
	s_mov_b32 m0, s6
	v_lshl_add_u64 v[234:235], s[72:73], 0, v[136:137]
	global_load_lds_dwordx4 v[232:233], off
	v_lshl_add_u64 v[232:233], s[82:83], 0, v[138:139]
	s_add_i32 m0, s6, 0x2000
	s_nop 0
	global_load_lds_dwordx4 v[232:233], off
	v_lshl_add_u64 v[232:233], s[72:73], 0, v[132:133]
	s_mov_b32 m0, s35
	s_nop 0
	global_load_lds_dwordx4 v[232:233], off
	s_mov_b32 m0, s54
	s_nop 0
	global_load_lds_dwordx4 v[234:235], off
	s_waitcnt vmcnt(8)
	s_waitcnt lgkmcnt(0)
	s_barrier
	s_waitcnt lgkmcnt(0)
	v_mfma_f32_16x16x32_bf16 v[64:67], v[152:155], v[200:203], 0
	v_mfma_f32_16x16x32_bf16 v[56:59], v[160:163], v[200:203], 0
	v_mfma_f32_16x16x32_bf16 v[48:51], v[152:155], v[208:211], 0
	v_mfma_f32_16x16x32_bf16 v[40:43], v[160:163], v[208:211], 0
	v_mfma_f32_16x16x32_bf16 v[32:35], v[152:155], v[216:219], 0
	v_mfma_f32_16x16x32_bf16 v[24:27], v[160:163], v[216:219], 0
	v_mfma_f32_16x16x32_bf16 v[16:19], v[152:155], v[224:227], 0
	v_mfma_f32_16x16x32_bf16 v[8:11], v[160:163], v[224:227], 0
	v_mfma_f32_16x16x32_bf16 v[64:67], v[156:159], v[204:207], v[64:67]
	v_mfma_f32_16x16x32_bf16 v[56:59], v[168:171], v[204:207], v[56:59]
	v_mfma_f32_16x16x32_bf16 v[48:51], v[156:159], v[212:215], v[48:51]
	v_mfma_f32_16x16x32_bf16 v[40:43], v[168:171], v[212:215], v[40:43]
	v_mfma_f32_16x16x32_bf16 v[32:35], v[156:159], v[220:223], v[32:35]
	v_mfma_f32_16x16x32_bf16 v[24:27], v[168:171], v[220:223], v[24:27]
	v_mfma_f32_16x16x32_bf16 v[16:19], v[156:159], v[228:231], v[16:19]
	v_mfma_f32_16x16x32_bf16 v[8:11], v[168:171], v[228:231], v[8:11]
	v_mfma_f32_16x16x32_bf16 v[60:63], v[174:177], v[200:203], 0
	v_mfma_f32_16x16x32_bf16 v[52:55], v[182:185], v[200:203], 0
	v_mfma_f32_16x16x32_bf16 v[44:47], v[174:177], v[208:211], 0
	v_mfma_f32_16x16x32_bf16 v[36:39], v[182:185], v[208:211], 0
	v_mfma_f32_16x16x32_bf16 v[28:31], v[174:177], v[216:219], 0
	v_mfma_f32_16x16x32_bf16 v[20:23], v[182:185], v[216:219], 0
	v_mfma_f32_16x16x32_bf16 v[12:15], v[174:177], v[224:227], 0
	v_mfma_f32_16x16x32_bf16 v[4:7], v[182:185], v[224:227], 0
	v_mfma_f32_16x16x32_bf16 v[60:63], v[178:181], v[204:207], v[60:63]
	v_mfma_f32_16x16x32_bf16 v[52:55], v[186:189], v[204:207], v[52:55]
	v_mfma_f32_16x16x32_bf16 v[44:47], v[178:181], v[212:215], v[44:47]
	v_mfma_f32_16x16x32_bf16 v[36:39], v[186:189], v[212:215], v[36:39]
	v_mfma_f32_16x16x32_bf16 v[28:31], v[178:181], v[220:223], v[28:31]
	v_mfma_f32_16x16x32_bf16 v[20:23], v[186:189], v[220:223], v[20:23]
	v_mfma_f32_16x16x32_bf16 v[12:15], v[178:181], v[228:231], v[12:15]
	v_mfma_f32_16x16x32_bf16 v[4:7], v[186:189], v[228:231], v[4:7]
	s_barrier
	s_add_i32 s6, 0, 0x18000
	v_add_u32_e32 v2, s6, v148
	s_add_i32 s33, 0, 0x1c000
	ds_read_b128 v[152:155], v2
	ds_read_b128 v[156:159], v2 offset:1024
	ds_read_b128 v[160:163], v2 offset:2048
	ds_read_b128 v[168:171], v2 offset:3072
	v_add_u32_e32 v2, s33, v148
	ds_read_b128 v[174:177], v2
	ds_read_b128 v[178:181], v2 offset:1024
	ds_read_b128 v[182:185], v2 offset:2048
	ds_read_b128 v[186:189], v2 offset:3072
	s_add_u32 s72, s72, 0x40000
	s_addc_u32 s73, s73, 0
	s_mov_b32 m0, s55
	v_lshl_add_u64 v[236:237], s[72:73], 0, v[132:133]
	ds_read_b128 v[200:203], v151 offset:32768
	ds_read_b128 v[204:207], v151 offset:33792
	ds_read_b128 v[208:211], v151 offset:34816
	ds_read_b128 v[212:215], v151 offset:35840
	ds_read_b128 v[216:219], v151 offset:36864
	ds_read_b128 v[220:223], v151 offset:37888
	ds_read_b128 v[224:227], v151 offset:38912
	ds_read_b128 v[228:231], v151 offset:39936
	global_load_lds_dwordx4 v[236:237], off
	v_lshl_add_u64 v[236:237], s[72:73], 0, v[136:137]
	s_mov_b32 m0, s56
	s_nop 0
	global_load_lds_dwordx4 v[236:237], off
	s_waitcnt vmcnt(8)
	s_waitcnt lgkmcnt(0)
	s_barrier
	s_waitcnt lgkmcnt(0)
	v_mfma_f32_16x16x32_bf16 v[128:131], v[152:155], v[200:203], v[128:131]
	v_mfma_f32_16x16x32_bf16 v[120:123], v[160:163], v[200:203], v[120:123]
	v_mfma_f32_16x16x32_bf16 v[112:115], v[152:155], v[208:211], v[112:115]
	v_mfma_f32_16x16x32_bf16 v[104:107], v[160:163], v[208:211], v[104:107]
	v_mfma_f32_16x16x32_bf16 v[96:99], v[152:155], v[216:219], v[96:99]
	v_mfma_f32_16x16x32_bf16 v[88:91], v[160:163], v[216:219], v[88:91]
	v_mfma_f32_16x16x32_bf16 v[80:83], v[152:155], v[224:227], v[80:83]
	v_mfma_f32_16x16x32_bf16 v[72:75], v[160:163], v[224:227], v[72:75]
	v_mfma_f32_16x16x32_bf16 v[128:131], v[156:159], v[204:207], v[128:131]
	v_mfma_f32_16x16x32_bf16 v[120:123], v[168:171], v[204:207], v[120:123]
	v_mfma_f32_16x16x32_bf16 v[112:115], v[156:159], v[212:215], v[112:115]
	v_mfma_f32_16x16x32_bf16 v[104:107], v[168:171], v[212:215], v[104:107]
	v_mfma_f32_16x16x32_bf16 v[96:99], v[156:159], v[220:223], v[96:99]
	v_mfma_f32_16x16x32_bf16 v[88:91], v[168:171], v[220:223], v[88:91]
	v_mfma_f32_16x16x32_bf16 v[80:83], v[156:159], v[228:231], v[80:83]
	v_mfma_f32_16x16x32_bf16 v[72:75], v[168:171], v[228:231], v[72:75]
	v_mfma_f32_16x16x32_bf16 v[124:127], v[174:177], v[200:203], v[124:127]
	v_mfma_f32_16x16x32_bf16 v[116:119], v[182:185], v[200:203], v[116:119]
	v_mfma_f32_16x16x32_bf16 v[108:111], v[174:177], v[208:211], v[108:111]
	v_mfma_f32_16x16x32_bf16 v[100:103], v[182:185], v[208:211], v[100:103]
	v_mfma_f32_16x16x32_bf16 v[92:95], v[174:177], v[216:219], v[92:95]
	v_mfma_f32_16x16x32_bf16 v[84:87], v[182:185], v[216:219], v[84:87]
	v_mfma_f32_16x16x32_bf16 v[76:79], v[174:177], v[224:227], v[76:79]
	v_mfma_f32_16x16x32_bf16 v[68:71], v[182:185], v[224:227], v[68:71]
	v_mfma_f32_16x16x32_bf16 v[124:127], v[178:181], v[204:207], v[124:127]
	v_mfma_f32_16x16x32_bf16 v[116:119], v[186:189], v[204:207], v[116:119]
	v_mfma_f32_16x16x32_bf16 v[108:111], v[178:181], v[212:215], v[108:111]
	v_mfma_f32_16x16x32_bf16 v[100:103], v[186:189], v[212:215], v[100:103]
	v_mfma_f32_16x16x32_bf16 v[92:95], v[178:181], v[220:223], v[92:95]
	v_mfma_f32_16x16x32_bf16 v[84:87], v[186:189], v[220:223], v[84:87]
	v_mfma_f32_16x16x32_bf16 v[76:79], v[178:181], v[228:231], v[76:79]
	v_mfma_f32_16x16x32_bf16 v[68:71], v[186:189], v[228:231], v[68:71]
	s_barrier
	s_add_i32 s6, s6, s20
	v_lshl_add_u64 v[146:147], v[146:147], 0, s[30:31]
	s_mov_b32 m0, s6
	ds_read_b128 v[200:203], v151 offset:49152
	ds_read_b128 v[204:207], v151 offset:50176
	ds_read_b128 v[208:211], v151 offset:51200
	ds_read_b128 v[212:215], v151 offset:52224
	ds_read_b128 v[216:219], v151 offset:53248
	ds_read_b128 v[220:223], v151 offset:54272
	ds_read_b128 v[224:227], v151 offset:55296
	ds_read_b128 v[228:231], v151 offset:56320
	global_load_lds_dwordx4 v[146:147], off
	s_add_i32 m0, s6, 0x2000
	s_add_u32 s70, s70, 0x40080
	v_lshl_add_u64 v[146:147], v[164:165], 0, s[30:31]
	s_addc_u32 s71, s71, 0
	s_add_i32 s6, s33, s20
	global_load_lds_dwordx4 v[146:147], off
	v_lshl_add_u64 v[146:147], s[70:71], 0, v[134:135]
	s_mov_b32 m0, s6
	s_nop 0
	global_load_lds_dwordx4 v[146:147], off
	v_lshl_add_u64 v[146:147], s[70:71], 0, v[138:139]
	s_add_i32 m0, s6, 0x2000
	s_nop 0
	global_load_lds_dwordx4 v[146:147], off
	v_lshl_add_u64 v[146:147], v[232:233], 0, s[30:31]
	s_mov_b32 m0, s76
	s_nop 0
	global_load_lds_dwordx4 v[146:147], off
	v_lshl_add_u64 v[146:147], v[234:235], 0, s[30:31]
	s_mov_b32 m0, s77
	s_nop 0
	global_load_lds_dwordx4 v[146:147], off
	s_waitcnt vmcnt(8)
	s_waitcnt lgkmcnt(0)
	s_barrier
	s_waitcnt lgkmcnt(0)
	v_mfma_f32_16x16x32_bf16 v[64:67], v[152:155], v[200:203], v[64:67]
	v_mfma_f32_16x16x32_bf16 v[56:59], v[160:163], v[200:203], v[56:59]
	v_mfma_f32_16x16x32_bf16 v[48:51], v[152:155], v[208:211], v[48:51]
	v_mfma_f32_16x16x32_bf16 v[40:43], v[160:163], v[208:211], v[40:43]
	v_mfma_f32_16x16x32_bf16 v[32:35], v[152:155], v[216:219], v[32:35]
	v_mfma_f32_16x16x32_bf16 v[24:27], v[160:163], v[216:219], v[24:27]
	v_mfma_f32_16x16x32_bf16 v[16:19], v[152:155], v[224:227], v[16:19]
	v_mfma_f32_16x16x32_bf16 v[8:11], v[160:163], v[224:227], v[8:11]
	v_mfma_f32_16x16x32_bf16 v[64:67], v[156:159], v[204:207], v[64:67]
	v_mfma_f32_16x16x32_bf16 v[56:59], v[168:171], v[204:207], v[56:59]
	v_mfma_f32_16x16x32_bf16 v[48:51], v[156:159], v[212:215], v[48:51]
	v_mfma_f32_16x16x32_bf16 v[40:43], v[168:171], v[212:215], v[40:43]
	v_mfma_f32_16x16x32_bf16 v[32:35], v[156:159], v[220:223], v[32:35]
	v_mfma_f32_16x16x32_bf16 v[24:27], v[168:171], v[220:223], v[24:27]
	v_mfma_f32_16x16x32_bf16 v[16:19], v[156:159], v[228:231], v[16:19]
	v_mfma_f32_16x16x32_bf16 v[8:11], v[168:171], v[228:231], v[8:11]
	v_mfma_f32_16x16x32_bf16 v[60:63], v[174:177], v[200:203], v[60:63]
	v_mfma_f32_16x16x32_bf16 v[52:55], v[182:185], v[200:203], v[52:55]
	v_mfma_f32_16x16x32_bf16 v[44:47], v[174:177], v[208:211], v[44:47]
	v_mfma_f32_16x16x32_bf16 v[36:39], v[182:185], v[208:211], v[36:39]
	v_mfma_f32_16x16x32_bf16 v[28:31], v[174:177], v[216:219], v[28:31]
	v_mfma_f32_16x16x32_bf16 v[20:23], v[182:185], v[216:219], v[20:23]
	v_mfma_f32_16x16x32_bf16 v[12:15], v[174:177], v[224:227], v[12:15]
	v_mfma_f32_16x16x32_bf16 v[4:7], v[182:185], v[224:227], v[4:7]
	v_mfma_f32_16x16x32_bf16 v[60:63], v[178:181], v[204:207], v[60:63]
	v_mfma_f32_16x16x32_bf16 v[52:55], v[186:189], v[204:207], v[52:55]
	v_mfma_f32_16x16x32_bf16 v[44:47], v[178:181], v[212:215], v[44:47]
	v_mfma_f32_16x16x32_bf16 v[36:39], v[186:189], v[212:215], v[36:39]
	v_mfma_f32_16x16x32_bf16 v[28:31], v[178:181], v[220:223], v[28:31]
	v_mfma_f32_16x16x32_bf16 v[20:23], v[186:189], v[220:223], v[20:23]
	v_mfma_f32_16x16x32_bf16 v[12:15], v[178:181], v[228:231], v[12:15]
	v_mfma_f32_16x16x32_bf16 v[4:7], v[186:189], v[228:231], v[4:7]
	s_barrier
	s_add_i32 s80, s80, 2
	s_add_u32 s68, s68, 0x100
	s_addc_u32 s69, s69, 0
	s_add_u32 s61, s61, 0x100
	s_addc_u32 s67, s67, 0

.Lh4_unit:
	s_lshl_b32 s98, s99, 14
	v_add_u32_e32 v6, s98, v151
	s_add_u32 s6, s68, 0xfffc0080
	s_addc_u32 s33, s69, -1
	s_add_i32 s82, 0, 0x10000
	s_cmp_eq_u32 s80, 12
	s_cselect_b32 s73, s10, s33
	s_cselect_b32 s72, s11, s6
	v_add_u32_e32 v2, s82, v148
	s_cselect_b32 s71, s15, s67
	s_cselect_b32 s70, s59, s61
	s_add_i32 s6, 0, 0x14000
	ds_read_b128 v[152:155], v2
	ds_read_b128 v[156:159], v2 offset:1024
	ds_read_b128 v[160:163], v2 offset:2048
	ds_read_b128 v[168:171], v2 offset:3072
	v_add_u32_e32 v2, s6, v148
	ds_read_b128 v[174:177], v2
	ds_read_b128 v[178:181], v2 offset:1024
	ds_read_b128 v[182:185], v2 offset:2048
	ds_read_b128 v[186:189], v2 offset:3072
	v_lshl_add_u64 v[146:147], s[68:69], 0, v[142:143]
	s_add_i32 m0, s35, 0xc000
	ds_read_b128 v[200:203], v6
	ds_read_b128 v[204:207], v6 offset:1024
	ds_read_b128 v[208:211], v6 offset:2048
	ds_read_b128 v[212:215], v6 offset:3072
	ds_read_b128 v[216:219], v6 offset:4096
	ds_read_b128 v[220:223], v6 offset:5120
	ds_read_b128 v[224:227], v6 offset:6144
	ds_read_b128 v[228:231], v6 offset:7168
	global_load_lds_dwordx4 v[146:147], off
	v_lshl_add_u64 v[146:147], s[68:69], 0, v[144:145]
	s_add_i32 m0, s35, 0xe000
	s_nop 0
	global_load_lds_dwordx4 v[146:147], off
	s_waitcnt vmcnt(8)
	s_waitcnt lgkmcnt(0)
	s_barrier
	s_waitcnt lgkmcnt(0)
	v_mfma_f32_16x16x32_bf16 v[128:131], v[152:155], v[200:203], 0
	v_mfma_f32_16x16x32_bf16 v[120:123], v[160:163], v[200:203], 0
	v_mfma_f32_16x16x32_bf16 v[112:115], v[152:155], v[208:211], 0
	v_mfma_f32_16x16x32_bf16 v[104:107], v[160:163], v[208:211], 0
	v_mfma_f32_16x16x32_bf16 v[96:99], v[152:155], v[216:219], 0
	v_mfma_f32_16x16x32_bf16 v[88:91], v[160:163], v[216:219], 0
	v_mfma_f32_16x16x32_bf16 v[80:83], v[152:155], v[224:227], 0
	v_mfma_f32_16x16x32_bf16 v[72:75], v[160:163], v[224:227], 0
	v_mfma_f32_16x16x32_bf16 v[128:131], v[156:159], v[204:207], v[128:131]
	v_mfma_f32_16x16x32_bf16 v[120:123], v[168:171], v[204:207], v[120:123]
	v_mfma_f32_16x16x32_bf16 v[112:115], v[156:159], v[212:215], v[112:115]
	v_mfma_f32_16x16x32_bf16 v[104:107], v[168:171], v[212:215], v[104:107]
	v_mfma_f32_16x16x32_bf16 v[96:99], v[156:159], v[220:223], v[96:99]
	v_mfma_f32_16x16x32_bf16 v[88:91], v[168:171], v[220:223], v[88:91]
	v_mfma_f32_16x16x32_bf16 v[80:83], v[156:159], v[228:231], v[80:83]
	v_mfma_f32_16x16x32_bf16 v[72:75], v[168:171], v[228:231], v[72:75]
	s_barrier
	s_add_i32 s33, s82, s20
	v_lshl_add_u64 v[146:147], s[70:71], 0, v[134:135]
	s_mov_b32 m0, s33
	global_load_lds_dwordx4 v[146:147], off
	s_add_i32 m0, s33, 0x2000
	s_add_u32 s82, s70, 0x40000
	v_lshl_add_u64 v[164:165], s[70:71], 0, v[138:139]
	s_addc_u32 s83, s71, 0
	s_add_i32 s6, s6, s20
	global_load_lds_dwordx4 v[164:165], off
	v_lshl_add_u64 v[232:233], s[82:83], 0, v[134:135]
	s_mov_b32 m0, s6
	v_lshl_add_u64 v[234:235], s[72:73], 0, v[136:137]
	global_load_lds_dwordx4 v[232:233], off
	v_lshl_add_u64 v[232:233], s[82:83], 0, v[138:139]
	s_add_i32 m0, s6, 0x2000
	s_nop 0
	global_load_lds_dwordx4 v[232:233], off
	v_lshl_add_u64 v[232:233], s[72:73], 0, v[132:133]
	s_mov_b32 m0, s35
	s_nop 0
	global_load_lds_dwordx4 v[232:233], off
	s_mov_b32 m0, s54
	s_nop 0
	global_load_lds_dwordx4 v[234:235], off
	s_waitcnt vmcnt(8)
	s_waitcnt lgkmcnt(0)
	s_barrier
	s_waitcnt lgkmcnt(0)
	v_mfma_f32_16x16x32_bf16 v[124:127], v[174:177], v[200:203], 0
	v_mfma_f32_16x16x32_bf16 v[116:119], v[182:185], v[200:203], 0
	v_mfma_f32_16x16x32_bf16 v[108:111], v[174:177], v[208:211], 0
	v_mfma_f32_16x16x32_bf16 v[100:103], v[182:185], v[208:211], 0
	v_mfma_f32_16x16x32_bf16 v[92:95], v[174:177], v[216:219], 0
	v_mfma_f32_16x16x32_bf16 v[84:87], v[182:185], v[216:219], 0
	v_mfma_f32_16x16x32_bf16 v[76:79], v[174:177], v[224:227], 0
	v_mfma_f32_16x16x32_bf16 v[68:71], v[182:185], v[224:227], 0
	v_mfma_f32_16x16x32_bf16 v[124:127], v[178:181], v[204:207], v[124:127]
	v_mfma_f32_16x16x32_bf16 v[116:119], v[186:189], v[204:207], v[116:119]
	v_mfma_f32_16x16x32_bf16 v[108:111], v[178:181], v[212:215], v[108:111]
	v_mfma_f32_16x16x32_bf16 v[100:103], v[186:189], v[212:215], v[100:103]
	v_mfma_f32_16x16x32_bf16 v[92:95], v[178:181], v[220:223], v[92:95]
	v_mfma_f32_16x16x32_bf16 v[84:87], v[186:189], v[220:223], v[84:87]
	v_mfma_f32_16x16x32_bf16 v[76:79], v[178:181], v[228:231], v[76:79]
	v_mfma_f32_16x16x32_bf16 v[68:71], v[186:189], v[228:231], v[68:71]
	s_barrier
	s_add_i32 s6, 0, 0x18000
	v_add_u32_e32 v2, s6, v148
	s_add_i32 s33, 0, 0x1c000
	ds_read_b128 v[152:155], v2
	ds_read_b128 v[156:159], v2 offset:1024
	ds_read_b128 v[160:163], v2 offset:2048
	ds_read_b128 v[168:171], v2 offset:3072
	v_add_u32_e32 v2, s33, v148
	ds_read_b128 v[174:177], v2
	ds_read_b128 v[178:181], v2 offset:1024
	ds_read_b128 v[182:185], v2 offset:2048
	ds_read_b128 v[186:189], v2 offset:3072
	s_add_u32 s72, s72, 0x40000
	s_addc_u32 s73, s73, 0
	s_mov_b32 m0, s55
	v_lshl_add_u64 v[236:237], s[72:73], 0, v[132:133]
	ds_read_b128 v[200:203], v6 offset:32768
	ds_read_b128 v[204:207], v6 offset:33792
	ds_read_b128 v[208:211], v6 offset:34816
	ds_read_b128 v[212:215], v6 offset:35840
	ds_read_b128 v[216:219], v6 offset:36864
	ds_read_b128 v[220:223], v6 offset:37888
	ds_read_b128 v[224:227], v6 offset:38912
	ds_read_b128 v[228:231], v6 offset:39936
	global_load_lds_dwordx4 v[236:237], off
	v_lshl_add_u64 v[236:237], s[72:73], 0, v[136:137]
	s_mov_b32 m0, s56
	s_nop 0
	global_load_lds_dwordx4 v[236:237], off
	s_waitcnt vmcnt(8)
	s_waitcnt lgkmcnt(0)
	s_barrier
	s_waitcnt lgkmcnt(0)
	v_mfma_f32_16x16x32_bf16 v[128:131], v[152:155], v[200:203], v[128:131]
	v_mfma_f32_16x16x32_bf16 v[120:123], v[160:163], v[200:203], v[120:123]
	v_mfma_f32_16x16x32_bf16 v[112:115], v[152:155], v[208:211], v[112:115]
	v_mfma_f32_16x16x32_bf16 v[104:107], v[160:163], v[208:211], v[104:107]
	v_mfma_f32_16x16x32_bf16 v[96:99], v[152:155], v[216:219], v[96:99]
	v_mfma_f32_16x16x32_bf16 v[88:91], v[160:163], v[216:219], v[88:91]
	v_mfma_f32_16x16x32_bf16 v[80:83], v[152:155], v[224:227], v[80:83]
	v_mfma_f32_16x16x32_bf16 v[72:75], v[160:163], v[224:227], v[72:75]
	v_mfma_f32_16x16x32_bf16 v[128:131], v[156:159], v[204:207], v[128:131]
	v_mfma_f32_16x16x32_bf16 v[120:123], v[168:171], v[204:207], v[120:123]
	v_mfma_f32_16x16x32_bf16 v[112:115], v[156:159], v[212:215], v[112:115]
	v_mfma_f32_16x16x32_bf16 v[104:107], v[168:171], v[212:215], v[104:107]
	v_mfma_f32_16x16x32_bf16 v[96:99], v[156:159], v[220:223], v[96:99]
	v_mfma_f32_16x16x32_bf16 v[88:91], v[168:171], v[220:223], v[88:91]
	v_mfma_f32_16x16x32_bf16 v[80:83], v[156:159], v[228:231], v[80:83]
	v_mfma_f32_16x16x32_bf16 v[72:75], v[168:171], v[228:231], v[72:75]
	s_barrier
	s_add_i32 s6, s6, s20
	v_lshl_add_u64 v[146:147], v[146:147], 0, s[30:31]
	s_mov_b32 m0, s6
	global_load_lds_dwordx4 v[146:147], off
	s_add_i32 m0, s6, 0x2000
	s_add_u32 s70, s70, 0x40080
	v_lshl_add_u64 v[146:147], v[164:165], 0, s[30:31]
	s_addc_u32 s71, s71, 0
	s_add_i32 s6, s33, s20
	global_load_lds_dwordx4 v[146:147], off
	v_lshl_add_u64 v[146:147], s[70:71], 0, v[134:135]
	s_mov_b32 m0, s6
	s_nop 0
	global_load_lds_dwordx4 v[146:147], off
	v_lshl_add_u64 v[146:147], s[70:71], 0, v[138:139]
	s_add_i32 m0, s6, 0x2000
	s_nop 0
	global_load_lds_dwordx4 v[146:147], off
	v_lshl_add_u64 v[146:147], v[232:233], 0, s[30:31]
	s_mov_b32 m0, s76
	s_nop 0
	global_load_lds_dwordx4 v[146:147], off
	v_lshl_add_u64 v[146:147], v[234:235], 0, s[30:31]
	s_mov_b32 m0, s77
	s_nop 0
	global_load_lds_dwordx4 v[146:147], off
	s_waitcnt vmcnt(8)
	s_waitcnt lgkmcnt(0)
	s_barrier
	s_waitcnt lgkmcnt(0)
	v_mfma_f32_16x16x32_bf16 v[124:127], v[174:177], v[200:203], v[124:127]
	v_mfma_f32_16x16x32_bf16 v[116:119], v[182:185], v[200:203], v[116:119]
	v_mfma_f32_16x16x32_bf16 v[108:111], v[174:177], v[208:211], v[108:111]
	v_mfma_f32_16x16x32_bf16 v[100:103], v[182:185], v[208:211], v[100:103]
	v_mfma_f32_16x16x32_bf16 v[92:95], v[174:177], v[216:219], v[92:95]
	v_mfma_f32_16x16x32_bf16 v[84:87], v[182:185], v[216:219], v[84:87]
	v_mfma_f32_16x16x32_bf16 v[76:79], v[174:177], v[224:227], v[76:79]
	v_mfma_f32_16x16x32_bf16 v[68:71], v[182:185], v[224:227], v[68:71]
	v_mfma_f32_16x16x32_bf16 v[124:127], v[178:181], v[204:207], v[124:127]
	v_mfma_f32_16x16x32_bf16 v[116:119], v[186:189], v[204:207], v[116:119]
	v_mfma_f32_16x16x32_bf16 v[108:111], v[178:181], v[212:215], v[108:111]
	v_mfma_f32_16x16x32_bf16 v[100:103], v[186:189], v[212:215], v[100:103]
	v_mfma_f32_16x16x32_bf16 v[92:95], v[178:181], v[220:223], v[92:95]
	v_mfma_f32_16x16x32_bf16 v[84:87], v[186:189], v[220:223], v[84:87]
	v_mfma_f32_16x16x32_bf16 v[76:79], v[178:181], v[228:231], v[76:79]
	v_mfma_f32_16x16x32_bf16 v[68:71], v[186:189], v[228:231], v[68:71]
	s_barrier
	s_add_i32 s80, s80, 2
	s_add_u32 s68, s68, 0x100
	s_addc_u32 s69, s69, 0
	s_add_u32 s61, s61, 0x100
	s_addc_u32 s67, s67, 0
.Lh4_loop:
	s_add_u32 s6, s68, 0xfffc0080
	s_addc_u32 s33, s69, -1
	s_add_i32 s82, 0, 0x10000
	s_cmp_eq_u32 s80, 12
	s_cselect_b32 s73, s10, s33
	s_cselect_b32 s72, s11, s6
	v_add_u32_e32 v2, s82, v148
	s_cselect_b32 s71, s15, s67
	s_cselect_b32 s70, s59, s61
	s_add_i32 s6, 0, 0x14000
	ds_read_b128 v[152:155], v2
	ds_read_b128 v[156:159], v2 offset:1024
	ds_read_b128 v[160:163], v2 offset:2048
	ds_read_b128 v[168:171], v2 offset:3072
	v_add_u32_e32 v2, s6, v148
	ds_read_b128 v[174:177], v2
	ds_read_b128 v[178:181], v2 offset:1024
	ds_read_b128 v[182:185], v2 offset:2048
	ds_read_b128 v[186:189], v2 offset:3072
	v_lshl_add_u64 v[146:147], s[68:69], 0, v[142:143]
	s_add_i32 m0, s35, 0xc000
	ds_read_b128 v[200:203], v6
	ds_read_b128 v[204:207], v6 offset:1024
	ds_read_b128 v[208:211], v6 offset:2048
	ds_read_b128 v[212:215], v6 offset:3072
	ds_read_b128 v[216:219], v6 offset:4096
	ds_read_b128 v[220:223], v6 offset:5120
	ds_read_b128 v[224:227], v6 offset:6144
	ds_read_b128 v[228:231], v6 offset:7168
	global_load_lds_dwordx4 v[146:147], off
	v_lshl_add_u64 v[146:147], s[68:69], 0, v[144:145]
	s_add_i32 m0, s35, 0xe000
	s_nop 0
	global_load_lds_dwordx4 v[146:147], off
	s_waitcnt vmcnt(8)
	s_waitcnt lgkmcnt(0)
	s_barrier
	s_waitcnt lgkmcnt(0)
	v_mfma_f32_16x16x32_bf16 v[128:131], v[152:155], v[200:203], v[128:131]
	v_mfma_f32_16x16x32_bf16 v[120:123], v[160:163], v[200:203], v[120:123]
	v_mfma_f32_16x16x32_bf16 v[112:115], v[152:155], v[208:211], v[112:115]
	v_mfma_f32_16x16x32_bf16 v[104:107], v[160:163], v[208:211], v[104:107]
	v_mfma_f32_16x16x32_bf16 v[96:99], v[152:155], v[216:219], v[96:99]
	v_mfma_f32_16x16x32_bf16 v[88:91], v[160:163], v[216:219], v[88:91]
	v_mfma_f32_16x16x32_bf16 v[80:83], v[152:155], v[224:227], v[80:83]
	v_mfma_f32_16x16x32_bf16 v[72:75], v[160:163], v[224:227], v[72:75]
	v_mfma_f32_16x16x32_bf16 v[128:131], v[156:159], v[204:207], v[128:131]
	v_mfma_f32_16x16x32_bf16 v[120:123], v[168:171], v[204:207], v[120:123]
	v_mfma_f32_16x16x32_bf16 v[112:115], v[156:159], v[212:215], v[112:115]
	v_mfma_f32_16x16x32_bf16 v[104:107], v[168:171], v[212:215], v[104:107]
	v_mfma_f32_16x16x32_bf16 v[96:99], v[156:159], v[220:223], v[96:99]
	v_mfma_f32_16x16x32_bf16 v[88:91], v[168:171], v[220:223], v[88:91]
	v_mfma_f32_16x16x32_bf16 v[80:83], v[156:159], v[228:231], v[80:83]
	v_mfma_f32_16x16x32_bf16 v[72:75], v[168:171], v[228:231], v[72:75]
	s_barrier
	s_add_i32 s33, s82, s20
	v_lshl_add_u64 v[146:147], s[70:71], 0, v[134:135]
	s_mov_b32 m0, s33
	global_load_lds_dwordx4 v[146:147], off
	s_add_i32 m0, s33, 0x2000
	s_add_u32 s82, s70, 0x40000
	v_lshl_add_u64 v[164:165], s[70:71], 0, v[138:139]
	s_addc_u32 s83, s71, 0
	s_add_i32 s6, s6, s20
	global_load_lds_dwordx4 v[164:165], off
	v_lshl_add_u64 v[232:233], s[82:83], 0, v[134:135]
	s_mov_b32 m0, s6
	v_lshl_add_u64 v[234:235], s[72:73], 0, v[136:137]
	global_load_lds_dwordx4 v[232:233], off
	v_lshl_add_u64 v[232:233], s[82:83], 0, v[138:139]
	s_add_i32 m0, s6, 0x2000
	s_nop 0
	global_load_lds_dwordx4 v[232:233], off
	v_lshl_add_u64 v[232:233], s[72:73], 0, v[132:133]
	s_mov_b32 m0, s35
	s_nop 0
	global_load_lds_dwordx4 v[232:233], off
	s_mov_b32 m0, s54
	s_nop 0
	global_load_lds_dwordx4 v[234:235], off
	s_waitcnt vmcnt(8)
	s_waitcnt lgkmcnt(0)
	s_barrier
	s_waitcnt lgkmcnt(0)
	v_mfma_f32_16x16x32_bf16 v[124:127], v[174:177], v[200:203], v[124:127]
	v_mfma_f32_16x16x32_bf16 v[116:119], v[182:185], v[200:203], v[116:119]
	v_mfma_f32_16x16x32_bf16 v[108:111], v[174:177], v[208:211], v[108:111]
	v_mfma_f32_16x16x32_bf16 v[100:103], v[182:185], v[208:211], v[100:103]
	v_mfma_f32_16x16x32_bf16 v[92:95], v[174:177], v[216:219], v[92:95]
	v_mfma_f32_16x16x32_bf16 v[84:87], v[182:185], v[216:219], v[84:87]
	v_mfma_f32_16x16x32_bf16 v[76:79], v[174:177], v[224:227], v[76:79]
	v_mfma_f32_16x16x32_bf16 v[68:71], v[182:185], v[224:227], v[68:71]
	v_mfma_f32_16x16x32_bf16 v[124:127], v[178:181], v[204:207], v[124:127]
	v_mfma_f32_16x16x32_bf16 v[116:119], v[186:189], v[204:207], v[116:119]
	v_mfma_f32_16x16x32_bf16 v[108:111], v[178:181], v[212:215], v[108:111]
	v_mfma_f32_16x16x32_bf16 v[100:103], v[186:189], v[212:215], v[100:103]
	v_mfma_f32_16x16x32_bf16 v[92:95], v[178:181], v[220:223], v[92:95]
	v_mfma_f32_16x16x32_bf16 v[84:87], v[186:189], v[220:223], v[84:87]
	v_mfma_f32_16x16x32_bf16 v[76:79], v[178:181], v[228:231], v[76:79]
	v_mfma_f32_16x16x32_bf16 v[68:71], v[186:189], v[228:231], v[68:71]
	s_barrier
	s_add_i32 s6, 0, 0x18000
	v_add_u32_e32 v2, s6, v148
	s_add_i32 s33, 0, 0x1c000
	ds_read_b128 v[152:155], v2
	ds_read_b128 v[156:159], v2 offset:1024
	ds_read_b128 v[160:163], v2 offset:2048
	ds_read_b128 v[168:171], v2 offset:3072
	v_add_u32_e32 v2, s33, v148
	ds_read_b128 v[174:177], v2
	ds_read_b128 v[178:181], v2 offset:1024
	ds_read_b128 v[182:185], v2 offset:2048
	ds_read_b128 v[186:189], v2 offset:3072
	s_add_u32 s72, s72, 0x40000
	s_addc_u32 s73, s73, 0
	s_mov_b32 m0, s55
	v_lshl_add_u64 v[236:237], s[72:73], 0, v[132:133]
	ds_read_b128 v[200:203], v6 offset:32768
	ds_read_b128 v[204:207], v6 offset:33792
	ds_read_b128 v[208:211], v6 offset:34816
	ds_read_b128 v[212:215], v6 offset:35840
	ds_read_b128 v[216:219], v6 offset:36864
	ds_read_b128 v[220:223], v6 offset:37888
	ds_read_b128 v[224:227], v6 offset:38912
	ds_read_b128 v[228:231], v6 offset:39936
	global_load_lds_dwordx4 v[236:237], off
	v_lshl_add_u64 v[236:237], s[72:73], 0, v[136:137]
	s_mov_b32 m0, s56
	s_nop 0
	global_load_lds_dwordx4 v[236:237], off
	s_waitcnt vmcnt(8)
	s_waitcnt lgkmcnt(0)
	s_barrier
	s_waitcnt lgkmcnt(0)
	v_mfma_f32_16x16x32_bf16 v[128:131], v[152:155], v[200:203], v[128:131]
	v_mfma_f32_16x16x32_bf16 v[120:123], v[160:163], v[200:203], v[120:123]
	v_mfma_f32_16x16x32_bf16 v[112:115], v[152:155], v[208:211], v[112:115]
	v_mfma_f32_16x16x32_bf16 v[104:107], v[160:163], v[208:211], v[104:107]
	v_mfma_f32_16x16x32_bf16 v[96:99], v[152:155], v[216:219], v[96:99]
	v_mfma_f32_16x16x32_bf16 v[88:91], v[160:163], v[216:219], v[88:91]
	v_mfma_f32_16x16x32_bf16 v[80:83], v[152:155], v[224:227], v[80:83]
	v_mfma_f32_16x16x32_bf16 v[72:75], v[160:163], v[224:227], v[72:75]
	v_mfma_f32_16x16x32_bf16 v[128:131], v[156:159], v[204:207], v[128:131]
	v_mfma_f32_16x16x32_bf16 v[120:123], v[168:171], v[204:207], v[120:123]
	v_mfma_f32_16x16x32_bf16 v[112:115], v[156:159], v[212:215], v[112:115]
	v_mfma_f32_16x16x32_bf16 v[104:107], v[168:171], v[212:215], v[104:107]
	v_mfma_f32_16x16x32_bf16 v[96:99], v[156:159], v[220:223], v[96:99]
	v_mfma_f32_16x16x32_bf16 v[88:91], v[168:171], v[220:223], v[88:91]
	v_mfma_f32_16x16x32_bf16 v[80:83], v[156:159], v[228:231], v[80:83]
	v_mfma_f32_16x16x32_bf16 v[72:75], v[168:171], v[228:231], v[72:75]
	s_barrier
	s_add_i32 s6, s6, s20
	v_lshl_add_u64 v[146:147], v[146:147], 0, s[30:31]
	s_mov_b32 m0, s6
	global_load_lds_dwordx4 v[146:147], off
	s_add_i32 m0, s6, 0x2000
	s_add_u32 s70, s70, 0x40080
	v_lshl_add_u64 v[146:147], v[164:165], 0, s[30:31]
	s_addc_u32 s71, s71, 0
	s_add_i32 s6, s33, s20
	global_load_lds_dwordx4 v[146:147], off
	v_lshl_add_u64 v[146:147], s[70:71], 0, v[134:135]
	s_mov_b32 m0, s6
	s_nop 0
	global_load_lds_dwordx4 v[146:147], off
	v_lshl_add_u64 v[146:147], s[70:71], 0, v[138:139]
	s_add_i32 m0, s6, 0x2000
	s_nop 0
	global_load_lds_dwordx4 v[146:147], off
	v_lshl_add_u64 v[146:147], v[232:233], 0, s[30:31]
	s_mov_b32 m0, s76
	s_nop 0
	global_load_lds_dwordx4 v[146:147], off
	v_lshl_add_u64 v[146:147], v[234:235], 0, s[30:31]
	s_mov_b32 m0, s77
	s_nop 0
	global_load_lds_dwordx4 v[146:147], off
	s_waitcnt vmcnt(8)
	s_waitcnt lgkmcnt(0)
	s_barrier
	s_waitcnt lgkmcnt(0)
	v_mfma_f32_16x16x32_bf16 v[124:127], v[174:177], v[200:203], v[124:127]
	v_mfma_f32_16x16x32_bf16 v[116:119], v[182:185], v[200:203], v[116:119]
	v_mfma_f32_16x16x32_bf16 v[108:111], v[174:177], v[208:211], v[108:111]
	v_mfma_f32_16x16x32_bf16 v[100:103], v[182:185], v[208:211], v[100:103]
	v_mfma_f32_16x16x32_bf16 v[92:95], v[174:177], v[216:219], v[92:95]
	v_mfma_f32_16x16x32_bf16 v[84:87], v[182:185], v[216:219], v[84:87]
	v_mfma_f32_16x16x32_bf16 v[76:79], v[174:177], v[224:227], v[76:79]
	v_mfma_f32_16x16x32_bf16 v[68:71], v[182:185], v[224:227], v[68:71]
	v_mfma_f32_16x16x32_bf16 v[124:127], v[178:181], v[204:207], v[124:127]
	v_mfma_f32_16x16x32_bf16 v[116:119], v[186:189], v[204:207], v[116:119]
	v_mfma_f32_16x16x32_bf16 v[108:111], v[178:181], v[212:215], v[108:111]
	v_mfma_f32_16x16x32_bf16 v[100:103], v[186:189], v[212:215], v[100:103]
	v_mfma_f32_16x16x32_bf16 v[92:95], v[178:181], v[220:223], v[92:95]
	v_mfma_f32_16x16x32_bf16 v[84:87], v[186:189], v[220:223], v[84:87]
	v_mfma_f32_16x16x32_bf16 v[76:79], v[178:181], v[228:231], v[76:79]
	v_mfma_f32_16x16x32_bf16 v[68:71], v[186:189], v[228:231], v[68:71]
	s_barrier
	s_add_i32 s80, s80, 2
	s_add_u32 s68, s68, 0x100
	s_addc_u32 s69, s69, 0
	s_add_u32 s61, s61, 0x100
	s_addc_u32 s67, s67, 0
	s_cmp_gt_u32 s80, 13
	s_cbranch_scc0 .Lh4_loop
	s_and_b64 vcc, exec, s[18:19]
	s_cbranch_vccz .Lh4_nb
	s_barrier
.Lh4_nb:
	s_lshr_b32 s6, s98, 5
	v_add_u32_e32 v8, s6, v149
	v_lshl_add_u32 v146, s66, 8, v141
	ds_read_b32 v216, v8
	ds_read_b32 v218, v8 offset:64
	ds_read_b32 v220, v8 offset:128
	ds_read_b32 v222, v8 offset:192
	s_lshl_b32 s6, s14, 7
	s_or_b32 s6, s6, s75
	s_ashr_i32 s10, s6, 6
	s_ashr_i32 s11, s10, 31
	s_lshl_b64 s[14:15], s[10:11], 21
	s_add_u32 s66, s57, s14
	s_addc_u32 s67, s74, s15
	v_lshlrev_b32_e32 v2, 1, v140
	v_lshl_add_u32 v212, v146, 7, v2
	v_add_u32_e32 v212, s98, v212
	v_add_u32_e32 v213, 0x1000, v212
	v_add_u32_e32 v214, 0x4000, v212
	v_add_u32_e32 v215, 0x5000, v212
	v_mov_b32_e32 v154, 0xbfb8aa3b
	v_mov_b32_e32 v156, 1.0
	s_waitcnt lgkmcnt(0)
	v_pk_mul_f32 v[128:129], v[128:129], v[216:217] op_sel_hi:[1,0]
	v_pk_mul_f32 v[130:131], v[130:131], v[216:217] op_sel_hi:[1,0]
	v_pk_mul_f32 v[120:121], v[120:121], v[216:217] op_sel_hi:[1,0]
	v_pk_mul_f32 v[122:123], v[122:123], v[216:217] op_sel_hi:[1,0]
	v_pk_mul_f32 v[124:125], v[124:125], v[216:217] op_sel_hi:[1,0]
	v_pk_mul_f32 v[126:127], v[126:127], v[216:217] op_sel_hi:[1,0]
	v_pk_mul_f32 v[116:117], v[116:117], v[216:217] op_sel_hi:[1,0]
	v_pk_mul_f32 v[118:119], v[118:119], v[216:217] op_sel_hi:[1,0]
	v_pk_mul_f32 v[200:201], v[128:129], v[154:155] op_sel_hi:[1,0]
	v_pk_mul_f32 v[202:203], v[130:131], v[154:155] op_sel_hi:[1,0]
	v_pk_mul_f32 v[204:205], v[120:121], v[154:155] op_sel_hi:[1,0]
	v_pk_mul_f32 v[206:207], v[122:123], v[154:155] op_sel_hi:[1,0]
	v_exp_f32_e32 v200, v200
	v_exp_f32_e32 v201, v201
	v_exp_f32_e32 v202, v202
	v_exp_f32_e32 v203, v203
	v_exp_f32_e32 v204, v204
	v_exp_f32_e32 v205, v205
	v_exp_f32_e32 v206, v206
	v_exp_f32_e32 v207, v207
	v_pk_add_f32 v[200:201], v[200:201], v[156:157] op_sel_hi:[1,0]
	v_pk_add_f32 v[202:203], v[202:203], v[156:157] op_sel_hi:[1,0]
	v_pk_add_f32 v[204:205], v[204:205], v[156:157] op_sel_hi:[1,0]
	v_pk_add_f32 v[206:207], v[206:207], v[156:157] op_sel_hi:[1,0]
	v_rcp_f32_e32 v200, v200
	v_rcp_f32_e32 v201, v201
	v_rcp_f32_e32 v202, v202
	v_rcp_f32_e32 v203, v203
	v_rcp_f32_e32 v204, v204
	v_rcp_f32_e32 v205, v205
	v_rcp_f32_e32 v206, v206
	v_rcp_f32_e32 v207, v207
	v_pk_mul_f32 v[128:129], v[128:129], v[200:201]
	v_pk_mul_f32 v[130:131], v[130:131], v[202:203]
	v_pk_mul_f32 v[120:121], v[120:121], v[204:205]
	v_pk_mul_f32 v[122:123], v[122:123], v[206:207]
	v_pk_mul_f32 v[128:129], v[128:129], v[124:125]
	v_pk_mul_f32 v[130:131], v[130:131], v[126:127]
	v_pk_mul_f32 v[120:121], v[120:121], v[116:117]
	v_pk_mul_f32 v[122:123], v[122:123], v[118:119]
	v_cvt_pk_bf16_f32 v208, v128, v129
	v_cvt_pk_bf16_f32 v209, v130, v131
	v_cvt_pk_bf16_f32 v210, v120, v121
	v_cvt_pk_bf16_f32 v211, v122, v123
	global_store_dwordx4 v212, v[208:211], s[66:67]
	v_pk_mul_f32 v[112:113], v[112:113], v[218:219] op_sel_hi:[1,0]
	v_pk_mul_f32 v[114:115], v[114:115], v[218:219] op_sel_hi:[1,0]
	v_pk_mul_f32 v[104:105], v[104:105], v[218:219] op_sel_hi:[1,0]
	v_pk_mul_f32 v[106:107], v[106:107], v[218:219] op_sel_hi:[1,0]
	v_pk_mul_f32 v[108:109], v[108:109], v[218:219] op_sel_hi:[1,0]
	v_pk_mul_f32 v[110:111], v[110:111], v[218:219] op_sel_hi:[1,0]
	v_pk_mul_f32 v[100:101], v[100:101], v[218:219] op_sel_hi:[1,0]
	v_pk_mul_f32 v[102:103], v[102:103], v[218:219] op_sel_hi:[1,0]
	v_pk_mul_f32 v[200:201], v[112:113], v[154:155] op_sel_hi:[1,0]
	v_pk_mul_f32 v[202:203], v[114:115], v[154:155] op_sel_hi:[1,0]
	v_pk_mul_f32 v[204:205], v[104:105], v[154:155] op_sel_hi:[1,0]
	v_pk_mul_f32 v[206:207], v[106:107], v[154:155] op_sel_hi:[1,0]
	v_exp_f32_e32 v200, v200
	v_exp_f32_e32 v201, v201
	v_exp_f32_e32 v202, v202
	v_exp_f32_e32 v203, v203
	v_exp_f32_e32 v204, v204
	v_exp_f32_e32 v205, v205
	v_exp_f32_e32 v206, v206
	v_exp_f32_e32 v207, v207
	v_pk_add_f32 v[200:201], v[200:201], v[156:157] op_sel_hi:[1,0]
	v_pk_add_f32 v[202:203], v[202:203], v[156:157] op_sel_hi:[1,0]
	v_pk_add_f32 v[204:205], v[204:205], v[156:157] op_sel_hi:[1,0]
	v_pk_add_f32 v[206:207], v[206:207], v[156:157] op_sel_hi:[1,0]
	v_rcp_f32_e32 v200, v200
	v_rcp_f32_e32 v201, v201
	v_rcp_f32_e32 v202, v202
	v_rcp_f32_e32 v203, v203
	v_rcp_f32_e32 v204, v204
	v_rcp_f32_e32 v205, v205
	v_rcp_f32_e32 v206, v206
	v_rcp_f32_e32 v207, v207
	v_pk_mul_f32 v[112:113], v[112:113], v[200:201]
	v_pk_mul_f32 v[114:115], v[114:115], v[202:203]
	v_pk_mul_f32 v[104:105], v[104:105], v[204:205]
	v_pk_mul_f32 v[106:107], v[106:107], v[206:207]
	v_pk_mul_f32 v[112:113], v[112:113], v[108:109]
	v_pk_mul_f32 v[114:115], v[114:115], v[110:111]
	v_pk_mul_f32 v[104:105], v[104:105], v[100:101]
	v_pk_mul_f32 v[106:107], v[106:107], v[102:103]
	v_cvt_pk_bf16_f32 v208, v112, v113
	v_cvt_pk_bf16_f32 v209, v114, v115
	v_cvt_pk_bf16_f32 v210, v104, v105
	v_cvt_pk_bf16_f32 v211, v106, v107
	global_store_dwordx4 v212, v[208:211], s[66:67] offset:2048
	v_pk_mul_f32 v[96:97], v[96:97], v[220:221] op_sel_hi:[1,0]
	v_pk_mul_f32 v[98:99], v[98:99], v[220:221] op_sel_hi:[1,0]
	v_pk_mul_f32 v[88:89], v[88:89], v[220:221] op_sel_hi:[1,0]
	v_pk_mul_f32 v[90:91], v[90:91], v[220:221] op_sel_hi:[1,0]
	v_pk_mul_f32 v[92:93], v[92:93], v[220:221] op_sel_hi:[1,0]
	v_pk_mul_f32 v[94:95], v[94:95], v[220:221] op_sel_hi:[1,0]
	v_pk_mul_f32 v[84:85], v[84:85], v[220:221] op_sel_hi:[1,0]
	v_pk_mul_f32 v[86:87], v[86:87], v[220:221] op_sel_hi:[1,0]
	v_pk_mul_f32 v[200:201], v[96:97], v[154:155] op_sel_hi:[1,0]
	v_pk_mul_f32 v[202:203], v[98:99], v[154:155] op_sel_hi:[1,0]
	v_pk_mul_f32 v[204:205], v[88:89], v[154:155] op_sel_hi:[1,0]
	v_pk_mul_f32 v[206:207], v[90:91], v[154:155] op_sel_hi:[1,0]
	v_exp_f32_e32 v200, v200
	v_exp_f32_e32 v201, v201
	v_exp_f32_e32 v202, v202
	v_exp_f32_e32 v203, v203
	v_exp_f32_e32 v204, v204
	v_exp_f32_e32 v205, v205
	v_exp_f32_e32 v206, v206
	v_exp_f32_e32 v207, v207
	v_pk_add_f32 v[200:201], v[200:201], v[156:157] op_sel_hi:[1,0]
	v_pk_add_f32 v[202:203], v[202:203], v[156:157] op_sel_hi:[1,0]
	v_pk_add_f32 v[204:205], v[204:205], v[156:157] op_sel_hi:[1,0]
	v_pk_add_f32 v[206:207], v[206:207], v[156:157] op_sel_hi:[1,0]
	v_rcp_f32_e32 v200, v200
	v_rcp_f32_e32 v201, v201
	v_rcp_f32_e32 v202, v202
	v_rcp_f32_e32 v203, v203
	v_rcp_f32_e32 v204, v204
	v_rcp_f32_e32 v205, v205
	v_rcp_f32_e32 v206, v206
	v_rcp_f32_e32 v207, v207
	v_pk_mul_f32 v[96:97], v[96:97], v[200:201]
	v_pk_mul_f32 v[98:99], v[98:99], v[202:203]
	v_pk_mul_f32 v[88:89], v[88:89], v[204:205]
	v_pk_mul_f32 v[90:91], v[90:91], v[206:207]
	v_pk_mul_f32 v[96:97], v[96:97], v[92:93]
	v_pk_mul_f32 v[98:99], v[98:99], v[94:95]
	v_pk_mul_f32 v[88:89], v[88:89], v[84:85]
	v_pk_mul_f32 v[90:91], v[90:91], v[86:87]
	v_cvt_pk_bf16_f32 v208, v96, v97
	v_cvt_pk_bf16_f32 v209, v98, v99
	v_cvt_pk_bf16_f32 v210, v88, v89
	v_cvt_pk_bf16_f32 v211, v90, v91
	global_store_dwordx4 v213, v[208:211], s[66:67]
	v_pk_mul_f32 v[80:81], v[80:81], v[222:223] op_sel_hi:[1,0]
	v_pk_mul_f32 v[82:83], v[82:83], v[222:223] op_sel_hi:[1,0]
	v_pk_mul_f32 v[72:73], v[72:73], v[222:223] op_sel_hi:[1,0]
	v_pk_mul_f32 v[74:75], v[74:75], v[222:223] op_sel_hi:[1,0]
	v_pk_mul_f32 v[76:77], v[76:77], v[222:223] op_sel_hi:[1,0]
	v_pk_mul_f32 v[78:79], v[78:79], v[222:223] op_sel_hi:[1,0]
	v_pk_mul_f32 v[68:69], v[68:69], v[222:223] op_sel_hi:[1,0]
	v_pk_mul_f32 v[70:71], v[70:71], v[222:223] op_sel_hi:[1,0]
	v_pk_mul_f32 v[200:201], v[80:81], v[154:155] op_sel_hi:[1,0]
	v_pk_mul_f32 v[202:203], v[82:83], v[154:155] op_sel_hi:[1,0]
	v_pk_mul_f32 v[204:205], v[72:73], v[154:155] op_sel_hi:[1,0]
	v_pk_mul_f32 v[206:207], v[74:75], v[154:155] op_sel_hi:[1,0]
	v_exp_f32_e32 v200, v200
	v_exp_f32_e32 v201, v201
	v_exp_f32_e32 v202, v202
	v_exp_f32_e32 v203, v203
	v_exp_f32_e32 v204, v204
	v_exp_f32_e32 v205, v205
	v_exp_f32_e32 v206, v206
	v_exp_f32_e32 v207, v207
	v_pk_add_f32 v[200:201], v[200:201], v[156:157] op_sel_hi:[1,0]
	v_pk_add_f32 v[202:203], v[202:203], v[156:157] op_sel_hi:[1,0]
	v_pk_add_f32 v[204:205], v[204:205], v[156:157] op_sel_hi:[1,0]
	v_pk_add_f32 v[206:207], v[206:207], v[156:157] op_sel_hi:[1,0]
	v_rcp_f32_e32 v200, v200
	v_rcp_f32_e32 v201, v201
	v_rcp_f32_e32 v202, v202
	v_rcp_f32_e32 v203, v203
	v_rcp_f32_e32 v204, v204
	v_rcp_f32_e32 v205, v205
	v_rcp_f32_e32 v206, v206
	v_rcp_f32_e32 v207, v207
	v_pk_mul_f32 v[80:81], v[80:81], v[200:201]
	v_pk_mul_f32 v[82:83], v[82:83], v[202:203]
	v_pk_mul_f32 v[72:73], v[72:73], v[204:205]
	v_pk_mul_f32 v[74:75], v[74:75], v[206:207]
	v_pk_mul_f32 v[80:81], v[80:81], v[76:77]
	v_pk_mul_f32 v[82:83], v[82:83], v[78:79]
	v_pk_mul_f32 v[72:73], v[72:73], v[68:69]
	v_pk_mul_f32 v[74:75], v[74:75], v[70:71]
	v_cvt_pk_bf16_f32 v208, v80, v81
	v_cvt_pk_bf16_f32 v209, v82, v83
	v_cvt_pk_bf16_f32 v210, v72, v73
	v_cvt_pk_bf16_f32 v211, v74, v75
	global_store_dwordx4 v213, v[208:211], s[66:67] offset:2048
	s_mov_b64 s[14:15], -1
	s_andn2_b64 vcc, exec, s[12:13]
	s_branch .Lp4_epi_tail
